# LRU early look-back loads: vmcnt(0) deferred to after the gates/scan barrier (results held in v236..v239), on top of the conv-stage wait relaxation
# baseline (speedup 1.0000x reference)
; #define LAS __attribute__((address_space(3)))
; __device__ __forceinline__ void lru_phase(LAS unsigned char* lds, const bf16* XB, const bf16* Y, bf16* HY, const bf16* WRt, const bf16* WIt,
;         const float* convw, const float* convb, const float* br, const float* bi, const float* lam, unsigned long long* gran, int G, int bid, int wave_s) {
;     ...
;         unsigned xa[2] = {0u, 0u}, xh[2] = {0u, 0u}, xt_[2] = {0u, 0u};
; #pragma unroll
;         for (int q = 0; q < 2; ++q) { const int kk = w + 8 * q;
;             if (kk < ch) { const unsigned long long* g = gran + ((size_t)(b * NCH + kk) * D + c0 + lane) * 2;
;                 const unsigned long long ya = __hip_atomic_load(g, __ATOMIC_RELAXED, __HIP_MEMORY_SCOPE_AGENT), yh = __hip_atomic_load(g + 1, __ATOMIC_RELAXED, __HIP_MEMORY_SCOPE_AGENT);
;                 xa[q] = (unsigned)ya; xh[q] = (unsigned)yh; xt_[q] = (unsigned)(ya >> 32) & (unsigned)(yh >> 32); } }
;         float av[16], uv[16];
;         const int c = lane, sg = 2 * rb + hi, tb = 32 * rb + 16 * hi;
;         {
;             f32x16 pr, pi;
; #pragma unroll
;             for (int i = 0; i < 16; ++i) { pr[i] = 0.f; pi[i] = 0.f; }
;             const int trow = 32 * rb + 16 * ((ql >> 2) & 1) + 4 * (ql >> 3) + (ql & 3);
; #pragma unroll
;             for (int s = 0; s < 4; ++s) {
;                 const bf16x8 af = *(const LAS bf16x8*)(xcB + trow * KP + 16 * s + 8 * hi);
;                 const bf16x8 wr_ = *(const LAS bf16x8*)(wL + d * KP + 16 * s + 8 * hi), wi_ = *(const LAS bf16x8*)(wL + (64 + d) * KP + 16 * s + 8 * hi);
;                 pr = __builtin_amdgcn_mfma_f32_32x32x16_bf16(af, wr_, pr, 0, 0, 0);
;                 pi = __builtin_amdgcn_mfma_f32_32x32x16_bf16(af, wi_, pi, 0, 0, 0);
;             }
;             const float brv = parL[320 + d], biv = parL[384 + d], ls8 = parL[448 + d];
;             float A = 1.f, H = 0.f;
; #pragma unroll
;             for (int i = 0; i < 16; ++i) {
;                 const float r = pg8::fast_sigmoid(pr[i] + brv), ig = pg8::fast_sigmoid(pi[i] + biv);
;                 const float la = ls8 * r;
;                 const float a = __builtin_amdgcn_exp2f(la * LOG2E);
;                 const float mult = __builtin_amdgcn_sqrtf(fmaxf(1.0f - a * a, 0.f));
;                 const float u = mult * ig * xcF[(tb + i) * 64 + d];
;                 av[i] = a; uv[i] = u; H = a * H + u; A *= a;
;             }
.LBB0_2140:
	s_bfe_u32 s82, s84, 0x30004
	s_ashr_i32 s94, s84, 7
	s_waitcnt lgkmcnt(0)
	s_barrier
	s_lshl_b32 s95, s82, 4
	v_or_b32_e32 v0, s91, v74
	s_cmp_lt_i32 s78, s94
	v_mov_b32_e32 v89, 0
	s_cselect_b64 s[62:63], -1, 0
	s_cmp_ge_i32 s78, s94
	v_lshlrev_b32_e32 v92, 4, v0
	v_mov_b32_e32 v95, 0
	v_mov_b32_e32 v96, 0
	v_mov_b32_e32 v236, 0
	v_mov_b32_e32 v237, 0
	v_mov_b32_e32 v94, 0
	s_cbranch_scc1 .LBB0_2142
	s_add_i32 s6, s95, s78
	s_ashr_i32 s7, s6, 31
	s_lshl_b64 s[6:7], s[6:7], 14
	s_add_u32 s6, s54, s6
	s_addc_u32 s7, s55, s7
	global_load_dwordx2 v[94:95], v92, s[6:7] sc1
	global_load_dwordx2 v[236:237], v92, s[6:7] offset:8 sc1
.LBB0_2142:
	s_cmp_lt_i32 s79, s94
	s_cselect_b64 s[60:61], -1, 0
	s_cmp_ge_i32 s79, s94
	v_mov_b32_e32 v90, 0
	v_mov_b32_e32 v238, 0
	v_mov_b32_e32 v239, 0
	v_mov_b32_e32 v88, 0
	s_cbranch_scc1 .LBB0_2144
	s_add_i32 s6, s95, s79
	s_ashr_i32 s7, s6, 31
	s_lshl_b64 s[6:7], s[6:7], 14
	s_add_u32 s6, s54, s6
	s_addc_u32 s7, s55, s7
	global_load_dwordx2 v[88:89], v92, s[6:7] sc1
	global_load_dwordx2 v[238:239], v92, s[6:7] offset:8 sc1
.LBB0_2144:
	ds_read_b128 v[0:3], v107
	ds_read_b128 v[4:7], v108 offset:32768
	ds_read_b128 v[208:211], v107 offset:32
	ds_read_b128 v[212:215], v108 offset:32800
	v_add_u32_e32 v86, v111, v119
	s_cmp_gt_i32 s94, 14
	s_waitcnt lgkmcnt(2)
	v_mfma_f32_32x32x16_bf16 v[16:31], v[0:3], v[4:7], 0
	ds_read_b128 v[4:7], v108 offset:41984
	ds_read_b128 v[216:219], v108 offset:42016
	s_cselect_b64 s[6:7], -1, 0
	s_or_b64 s[6:7], s[56:57], s[6:7]
	s_and_b64 vcc, exec, s[6:7]
	s_waitcnt lgkmcnt(1)
	v_mfma_f32_32x32x16_bf16 v[0:15], v[0:3], v[4:7], 0
	v_mfma_f32_32x32x16_bf16 v[16:31], v[208:211], v[212:215], v[16:31]
	s_waitcnt lgkmcnt(0)
	v_mfma_f32_32x32x16_bf16 v[0:15], v[208:211], v[216:219], v[0:15]
	ds_read_b128 v[208:211], v107 offset:64
	ds_read_b128 v[212:215], v108 offset:32832
	ds_read_b128 v[216:219], v107 offset:96
	ds_read_b128 v[220:223], v108 offset:32864
	s_waitcnt lgkmcnt(2)
	v_mfma_f32_32x32x16_bf16 v[16:31], v[208:211], v[212:215], v[16:31]
	ds_read_b128 v[212:215], v108 offset:42048
	ds_read_b128 v[224:227], v108 offset:42080
	ds_read2st64_b32 v[98:99], v110 offset0:5 offset1:6
	ds_read_b32 v65, v110 offset:1792
	ds_read_b32 v86, v86
	ds_read_b32 v91, v191
	ds_read_b32 v93, v192
	ds_read_b32 v97, v193
	ds_read_b32 v174, v194
	ds_read_b32 v228, v195
	s_waitcnt lgkmcnt(10)
	v_mfma_f32_32x32x16_bf16 v[16:31], v[216:219], v[220:223], v[16:31]
	s_waitcnt lgkmcnt(9)
	v_mfma_f32_32x32x16_bf16 v[0:15], v[208:211], v[212:215], v[0:15]
	s_waitcnt lgkmcnt(7)
	s_nop 8
	v_add_f32_e32 v16, v16, v98
	v_mul_f32_e32 v16, 0xbfb8aa3b, v16
	v_exp_f32_e32 v16, v16
	v_add_f32_e32 v18, v18, v98
	v_mul_f32_e32 v18, 0xbfb8aa3b, v18
	v_exp_f32_e32 v18, v18
	v_add_f32_e32 v16, 1.0, v16
	v_rcp_f32_e32 v16, v16
	v_mfma_f32_32x32x16_bf16 v[0:15], v[216:219], v[224:227], v[0:15]
	s_waitcnt lgkmcnt(6)
	v_mul_f32_e32 v16, v65, v16
	v_mul_f32_e32 v16, 0x3fb8aa3b, v16
	v_exp_f32_e32 v207, v16
	v_add_f32_e32 v16, v17, v98
	v_mul_f32_e32 v16, 0xbfb8aa3b, v16
	v_exp_f32_e32 v16, v16
	s_nop 4
	v_add_f32_e32 v0, v0, v99
	v_mul_f32_e32 v0, 0xbfb8aa3b, v0
	v_exp_f32_e32 v0, v0
	v_add_f32_e32 v16, 1.0, v16
	v_rcp_f32_e32 v16, v16
	v_fma_f32 v17, -v207, v207, 1.0
	v_add_f32_e32 v0, 1.0, v0
	v_max_f32_e32 v17, 0, v17
	v_mul_f32_e32 v16, v65, v16
	v_mul_f32_e32 v16, 0x3fb8aa3b, v16
	v_rcp_f32_e32 v0, v0
	v_exp_f32_e32 v208, v16
	v_sqrt_f32_e32 v16, v17
	v_add_f32_e32 v1, v1, v99
	v_mul_f32_e32 v1, 0xbfb8aa3b, v1
	v_exp_f32_e32 v1, v1
	v_mul_f32_e32 v0, v0, v16
	v_add_f32_e32 v16, 1.0, v18
	v_rcp_f32_e32 v16, v16
	v_fma_f32 v17, -v208, v208, 1.0
	v_add_f32_e32 v1, 1.0, v1
	v_max_f32_e32 v17, 0, v17
	v_add_f32_e32 v2, v2, v99
	v_mul_f32_e32 v16, v65, v16
	v_rcp_f32_e32 v1, v1
	v_sqrt_f32_e32 v17, v17
	v_mul_f32_e32 v2, 0xbfb8aa3b, v2
	v_mul_f32_e32 v16, 0x3fb8aa3b, v16
	v_exp_f32_e32 v2, v2
	v_exp_f32_e32 v210, v16
	v_mul_f32_e32 v1, v1, v17
	s_waitcnt lgkmcnt(4)
	v_mul_f32_e32 v211, v91, v1
	v_add_f32_e32 v1, 1.0, v2
	v_fma_f32 v2, -v210, v210, 1.0
	v_add_f32_e32 v16, v19, v98
	v_max_f32_e32 v2, 0, v2
	v_mul_f32_e32 v16, 0xbfb8aa3b, v16
	v_rcp_f32_e32 v1, v1
	v_sqrt_f32_e32 v2, v2
	v_exp_f32_e32 v16, v16
	v_add_f32_e32 v3, v3, v99
	v_mul_f32_e32 v3, 0xbfb8aa3b, v3
	v_mul_f32_e32 v1, v1, v2
	v_add_f32_e32 v2, 1.0, v16
	v_rcp_f32_e32 v2, v2
	v_exp_f32_e32 v3, v3
	s_waitcnt lgkmcnt(3)
	v_mul_f32_e32 v213, v93, v1
	v_mul_f32_e32 v17, v207, v208
	v_mul_f32_e32 v2, v65, v2
	v_mul_f32_e32 v2, 0x3fb8aa3b, v2
	v_exp_f32_e32 v212, v2
	v_add_f32_e32 v1, 1.0, v3
	v_add_f32_e32 v3, v20, v98
	v_mul_f32_e32 v3, 0xbfb8aa3b, v3
	v_fma_f32 v2, -v212, v212, 1.0
	v_max_f32_e32 v2, 0, v2
	v_rcp_f32_e32 v1, v1
	v_sqrt_f32_e32 v2, v2
	v_exp_f32_e32 v3, v3
	v_mul_f32_e32 v16, v210, v17
	v_mul_f32_e32 v209, v86, v0
	v_mul_f32_e32 v1, v1, v2
	v_add_f32_e32 v2, 1.0, v3
	v_rcp_f32_e32 v2, v2
	v_add_f32_e32 v3, v4, v99
	v_mul_f32_e32 v3, 0xbfb8aa3b, v3
	v_exp_f32_e32 v3, v3
	v_mul_f32_e32 v2, v65, v2
	v_mul_f32_e32 v2, 0x3fb8aa3b, v2
	v_exp_f32_e32 v214, v2
	s_waitcnt lgkmcnt(2)
	v_mul_f32_e32 v215, v97, v1
	v_add_f32_e32 v1, 1.0, v3
	v_add_f32_e32 v3, v21, v98
	v_fma_f32 v2, -v214, v214, 1.0
	v_max_f32_e32 v2, 0, v2
	v_mul_f32_e32 v3, 0xbfb8aa3b, v3
	v_rcp_f32_e32 v1, v1
	v_sqrt_f32_e32 v2, v2
	v_exp_f32_e32 v3, v3
	v_mul_f32_e32 v4, v212, v16
	v_fma_f32 v0, 0, v207, v209
	v_mul_f32_e32 v1, v1, v2
	v_add_f32_e32 v2, 1.0, v3
	v_rcp_f32_e32 v2, v2
	v_add_f32_e32 v3, v5, v99
	v_mul_f32_e32 v3, 0xbfb8aa3b, v3
	v_exp_f32_e32 v3, v3
	v_mul_f32_e32 v2, v65, v2
	v_mul_f32_e32 v2, 0x3fb8aa3b, v2
	v_exp_f32_e32 v216, v2
	s_waitcnt lgkmcnt(1)
; __device__ __forceinline__ float fast_sigmoid(float v) { return __builtin_amdgcn_rcpf(1.0f + __builtin_amdgcn_exp2f(-1.44269504089f * v)); }
; #define LDS_BARRIER() do { asm volatile("s_waitcnt lgkmcnt(0)" ::: "memory"); __builtin_amdgcn_s_barrier(); asm volatile("" ::: "memory"); } while (0)
; __device__ __forceinline__ void lru_phase(LAS unsigned char* lds, const bf16* XB, const bf16* Y, bf16* HY, const bf16* WRt, const bf16* WIt,
;         const float* convw, const float* convb, const float* br, const float* bi, const float* lam, unsigned long long* gran, int G, int bid, int wave_s) {
;     ...
;         for (int q = 0; q < 2; ++q) { const int kk = w + 8 * q;
;             if (kk < ch) { const unsigned long long* g = gran + ((size_t)(b * NCH + kk) * D + c0 + lane) * 2;
;                 const unsigned long long ya = __hip_atomic_load(g, __ATOMIC_RELAXED, __HIP_MEMORY_SCOPE_AGENT), yh = __hip_atomic_load(g + 1, __ATOMIC_RELAXED, __HIP_MEMORY_SCOPE_AGENT);
;                 xa[q] = (unsigned)ya; xh[q] = (unsigned)yh; xt_[q] = (unsigned)(ya >> 32) & (unsigned)(yh >> 32); } }
;     ...
;             for (int i = 0; i < 16; ++i) {
;                 const float r = pg8::fast_sigmoid(pr[i] + brv), ig = pg8::fast_sigmoid(pi[i] + biv);
;                 const float la = ls8 * r;
;                 const float a = __builtin_amdgcn_exp2f(la * LOG2E);
;                 const float mult = __builtin_amdgcn_sqrtf(fmaxf(1.0f - a * a, 0.f));
;                 const float u = mult * ig * xcF[(tb + i) * 64 + d];
;                 av[i] = a; uv[i] = u; H = a * H + u; A *= a;
;             }
;             segA[sg * 64 + d] = A; segH[sg * 64 + d] = H;
;         }
;         LDS_BARRIER();
	v_mul_f32_e32 v217, v174, v1
	v_add_f32_e32 v1, 1.0, v3
	v_add_f32_e32 v3, v22, v98
	v_fma_f32 v2, -v216, v216, 1.0
	v_max_f32_e32 v2, 0, v2
	v_mul_f32_e32 v3, 0xbfb8aa3b, v3
	v_rcp_f32_e32 v1, v1
	v_sqrt_f32_e32 v2, v2
	v_exp_f32_e32 v3, v3
	v_fma_f32 v0, v208, v0, v211
	v_fma_f32 v0, v210, v0, v213
	v_mul_f32_e32 v1, v1, v2
	v_add_f32_e32 v2, 1.0, v3
	v_rcp_f32_e32 v2, v2
	v_add_f32_e32 v3, v6, v99
	v_mul_f32_e32 v3, 0xbfb8aa3b, v3
	v_exp_f32_e32 v3, v3
	v_mul_f32_e32 v2, v65, v2
	v_mul_f32_e32 v2, 0x3fb8aa3b, v2
	v_exp_f32_e32 v218, v2
	s_waitcnt lgkmcnt(0)
	v_mul_f32_e32 v219, v228, v1
	v_add_f32_e32 v1, 1.0, v3
	v_add_f32_e32 v3, v23, v98
	v_fma_f32 v2, -v218, v218, 1.0
	v_max_f32_e32 v2, 0, v2
	v_mul_f32_e32 v3, 0xbfb8aa3b, v3
	v_rcp_f32_e32 v1, v1
	v_sqrt_f32_e32 v2, v2
	v_exp_f32_e32 v3, v3
	v_fma_f32 v0, v212, v0, v215
	v_mul_f32_e32 v4, v214, v4
	v_mul_f32_e32 v1, v1, v2
	v_add_f32_e32 v2, 1.0, v3
	v_rcp_f32_e32 v2, v2
	v_add_f32_e32 v3, v7, v99
	v_mul_f32_e32 v3, 0xbfb8aa3b, v3
	v_exp_f32_e32 v3, v3
	v_mul_f32_e32 v2, v65, v2
	v_mul_f32_e32 v2, 0x3fb8aa3b, v2
	v_exp_f32_e32 v220, v2
	ds_read_b32 v2, v196
	ds_read_b32 v5, v197
	ds_read_b32 v6, v198
	ds_read_b32 v7, v199
	ds_read_b32 v16, v200
	ds_read_b32 v17, v201
	ds_read_b32 v18, v202
	ds_read_b32 v19, v203
	s_waitcnt lgkmcnt(7)
	v_mul_f32_e32 v221, v2, v1
	v_add_f32_e32 v1, 1.0, v3
	v_fma_f32 v2, -v220, v220, 1.0
	v_add_f32_e32 v3, v24, v98
	v_max_f32_e32 v2, 0, v2
	v_mul_f32_e32 v3, 0xbfb8aa3b, v3
	v_rcp_f32_e32 v1, v1
	v_sqrt_f32_e32 v2, v2
	v_exp_f32_e32 v3, v3
	v_fma_f32 v0, v214, v0, v217
	v_mul_f32_e32 v4, v216, v4
	v_mul_f32_e32 v1, v1, v2
	v_add_f32_e32 v2, 1.0, v3
	v_rcp_f32_e32 v2, v2
	v_add_f32_e32 v3, v8, v99
	v_mul_f32_e32 v3, 0xbfb8aa3b, v3
	v_exp_f32_e32 v3, v3
	v_mul_f32_e32 v2, v65, v2
	v_mul_f32_e32 v2, 0x3fb8aa3b, v2
	v_exp_f32_e32 v225, v2
	s_waitcnt lgkmcnt(6)
	v_mul_f32_e32 v227, v5, v1
	v_add_f32_e32 v1, 1.0, v3
	v_add_f32_e32 v3, v25, v98
	v_fma_f32 v2, -v225, v225, 1.0
	v_max_f32_e32 v2, 0, v2
	v_mul_f32_e32 v3, 0xbfb8aa3b, v3
	v_rcp_f32_e32 v1, v1
	v_sqrt_f32_e32 v2, v2
	v_exp_f32_e32 v3, v3
	v_fma_f32 v0, v216, v0, v219
	v_mul_f32_e32 v4, v218, v4
	v_mul_f32_e32 v1, v1, v2
	v_add_f32_e32 v2, 1.0, v3
	v_rcp_f32_e32 v2, v2
	v_add_f32_e32 v3, v9, v99
	v_mul_f32_e32 v3, 0xbfb8aa3b, v3
	v_exp_f32_e32 v3, v3
	v_mul_f32_e32 v2, v65, v2
	v_mul_f32_e32 v2, 0x3fb8aa3b, v2
	v_exp_f32_e32 v230, v2
	s_waitcnt lgkmcnt(5)
	v_mul_f32_e32 v231, v6, v1
	v_add_f32_e32 v1, 1.0, v3
	v_add_f32_e32 v3, v26, v98
	v_fma_f32 v2, -v230, v230, 1.0
	v_max_f32_e32 v2, 0, v2
	v_mul_f32_e32 v3, 0xbfb8aa3b, v3
	v_rcp_f32_e32 v1, v1
	v_sqrt_f32_e32 v2, v2
	v_exp_f32_e32 v3, v3
	v_fma_f32 v0, v218, v0, v221
	v_mul_f32_e32 v4, v220, v4
	v_mul_f32_e32 v1, v1, v2
	v_add_f32_e32 v2, 1.0, v3
	v_rcp_f32_e32 v2, v2
	v_add_f32_e32 v3, v10, v99
	v_mul_f32_e32 v3, 0xbfb8aa3b, v3
	v_exp_f32_e32 v3, v3
	v_mul_f32_e32 v2, v65, v2
	v_mul_f32_e32 v2, 0x3fb8aa3b, v2
	v_exp_f32_e32 v233, v2
	s_waitcnt lgkmcnt(4)
	v_mul_f32_e32 v234, v7, v1
	v_add_f32_e32 v1, 1.0, v3
	v_add_f32_e32 v3, v27, v98
	v_fma_f32 v2, -v233, v233, 1.0
	v_max_f32_e32 v2, 0, v2
	v_mul_f32_e32 v3, 0xbfb8aa3b, v3
	v_rcp_f32_e32 v1, v1
	v_sqrt_f32_e32 v2, v2
	v_exp_f32_e32 v3, v3
	v_fma_f32 v0, v220, v0, v227
	v_mul_f32_e32 v4, v225, v4
	v_mul_f32_e32 v1, v1, v2
	v_add_f32_e32 v2, 1.0, v3
	v_rcp_f32_e32 v2, v2
	v_add_f32_e32 v3, v11, v99
	v_mul_f32_e32 v3, 0xbfb8aa3b, v3
	v_exp_f32_e32 v3, v3
	v_mul_f32_e32 v2, v65, v2
	v_mul_f32_e32 v2, 0x3fb8aa3b, v2
	v_exp_f32_e32 v224, v2
	s_waitcnt lgkmcnt(3)
	v_mul_f32_e32 v226, v1, v16
	v_add_f32_e32 v1, 1.0, v3
	v_add_f32_e32 v3, v28, v98
	v_fma_f32 v2, -v224, v224, 1.0
	v_max_f32_e32 v2, 0, v2
	v_mul_f32_e32 v3, 0xbfb8aa3b, v3
	v_rcp_f32_e32 v1, v1
	v_sqrt_f32_e32 v2, v2
	v_exp_f32_e32 v3, v3
	v_fma_f32 v0, v225, v0, v231
	v_mul_f32_e32 v4, v230, v4
	v_mul_f32_e32 v1, v1, v2
	v_add_f32_e32 v2, 1.0, v3
	v_rcp_f32_e32 v2, v2
	v_add_f32_e32 v3, v12, v99
	v_mul_f32_e32 v3, 0xbfb8aa3b, v3
	v_exp_f32_e32 v3, v3
	v_mul_f32_e32 v2, v65, v2
	v_mul_f32_e32 v2, 0x3fb8aa3b, v2
	v_exp_f32_e32 v222, v2
	s_waitcnt lgkmcnt(2)
	v_mul_f32_e32 v223, v1, v17
	v_add_f32_e32 v1, 1.0, v3
	v_add_f32_e32 v3, v29, v98
	v_fma_f32 v2, -v222, v222, 1.0
	v_max_f32_e32 v2, 0, v2
	v_mul_f32_e32 v3, 0xbfb8aa3b, v3
	v_rcp_f32_e32 v1, v1
	v_sqrt_f32_e32 v2, v2
	v_exp_f32_e32 v3, v3
	v_fma_f32 v0, v230, v0, v234
	v_mul_f32_e32 v4, v233, v4
	v_mul_f32_e32 v1, v1, v2
	v_add_f32_e32 v2, 1.0, v3
	v_rcp_f32_e32 v2, v2
	v_add_f32_e32 v3, v13, v99
	v_mul_f32_e32 v3, 0xbfb8aa3b, v3
	v_exp_f32_e32 v3, v3
	v_mul_f32_e32 v2, v65, v2
	v_mul_f32_e32 v2, 0x3fb8aa3b, v2
	v_exp_f32_e32 v228, v2
	s_waitcnt lgkmcnt(1)
	v_mul_f32_e32 v229, v1, v18
	v_add_f32_e32 v1, 1.0, v3
	v_add_f32_e32 v3, v30, v98
	v_fma_f32 v2, -v228, v228, 1.0
	v_max_f32_e32 v2, 0, v2
	v_mul_f32_e32 v3, 0xbfb8aa3b, v3
	v_rcp_f32_e32 v1, v1
	v_sqrt_f32_e32 v2, v2
	v_exp_f32_e32 v3, v3
	ds_read_b32 v6, v205
	v_fma_f32 v0, v233, v0, v226
	v_mul_f32_e32 v1, v1, v2
	v_add_f32_e32 v2, 1.0, v3
	v_rcp_f32_e32 v2, v2
	v_add_f32_e32 v3, v14, v99
	v_mul_f32_e32 v3, 0xbfb8aa3b, v3
	v_exp_f32_e32 v3, v3
	v_mul_f32_e32 v2, v65, v2
	v_mul_f32_e32 v2, 0x3fb8aa3b, v2
	v_exp_f32_e32 v30, v2
	s_waitcnt lgkmcnt(1)
	v_mul_f32_e32 v232, v1, v19
	v_add_f32_e32 v1, 1.0, v3
	v_add_f32_e32 v3, v31, v98
	v_fma_f32 v2, -v30, v30, 1.0
	v_max_f32_e32 v2, 0, v2
	v_mul_f32_e32 v3, 0xbfb8aa3b, v3
	v_rcp_f32_e32 v1, v1
	v_sqrt_f32_e32 v2, v2
	v_exp_f32_e32 v3, v3
	v_mul_f32_e32 v4, v224, v4
	v_fma_f32 v0, v224, v0, v223
	v_mul_f32_e32 v1, v1, v2
	v_add_f32_e32 v2, 1.0, v3
	v_rcp_f32_e32 v2, v2
	v_add_f32_e32 v3, v15, v99
	v_mul_f32_e32 v3, 0xbfb8aa3b, v3
	v_exp_f32_e32 v3, v3
	v_mul_f32_e32 v2, v65, v2
	v_mul_f32_e32 v2, 0x3fb8aa3b, v2
	v_exp_f32_e32 v31, v2
	ds_read_b32 v2, v204
	v_add_f32_e32 v3, 1.0, v3
	v_rcp_f32_e32 v3, v3
	v_fma_f32 v5, -v31, v31, 1.0
	v_max_f32_e32 v5, 0, v5
	v_sqrt_f32_e32 v5, v5
	v_mul_f32_e32 v4, v222, v4
	v_fma_f32 v0, v222, v0, v229
	v_mul_f32_e32 v4, v228, v4
	v_fma_f32 v0, v228, v0, v232
	s_waitcnt lgkmcnt(0)
	v_mul_f32_e32 v98, v1, v2
	v_mul_f32_e32 v1, v30, v4
	v_mul_f32_e32 v2, v3, v5
	v_fma_f32 v0, v30, v0, v98
	v_mul_f32_e32 v99, v2, v6
	v_mul_f32_e32 v1, v31, v1
	v_fma_f32 v0, v31, v0, v99
	ds_write_b32 v112, v1
	ds_write_b32 v113, v0
	s_waitcnt lgkmcnt(0)
	s_barrier
	s_waitcnt vmcnt(0)
	v_and_b32_e32 v95, v237, v95
	v_mov_b32_e32 v96, v236
	v_and_b32_e32 v89, v239, v89
	v_mov_b32_e32 v90, v238
	s_cbranch_vccz .LBB0_2147
	s_andn2_b64 vcc, exec, s[62:63]
	s_cbranch_vccz .LBB0_2148
